# union + static s_setprio 1 for lagging attention waves
# baseline (speedup 1.0000x reference)
.Lattn_lag:
	s_setprio 1
	v_lshl_add_u32 v0, s52, 14, v234
	ds_read_b128 v[130:133], v0 offset:49152
	ds_read_b128 v[134:137], v0 offset:50176
	ds_read_b128 v[138:141], v0 offset:51200
	ds_read_b128 v[142:145], v0 offset:52224
	s_waitcnt lgkmcnt(3)
	v_mfma_f32_16x16x32_bf16 v[110:113], v[130:133], v[114:117], v[110:113]
	v_mfma_f32_16x16x32_bf16 v[30:33], v[130:133], v[122:125], v[30:33]
	s_waitcnt lgkmcnt(2)
	v_mfma_f32_16x16x32_bf16 v[110:113], v[134:137], v[118:121], v[110:113]
	v_mfma_f32_16x16x32_bf16 v[30:33], v[134:137], v[126:129], v[30:33]
	ds_read_b128 v[130:133], v0 offset:53248
	ds_read_b128 v[134:137], v0 offset:54272
	s_waitcnt lgkmcnt(2)
	v_mfma_f32_16x16x32_bf16 v[106:109], v[138:141], v[114:117], v[106:109]
	v_mfma_f32_16x16x32_bf16 v[26:29], v[138:141], v[122:125], v[26:29]
	v_mfma_f32_16x16x32_bf16 v[106:109], v[142:145], v[118:121], v[106:109]
	v_mfma_f32_16x16x32_bf16 v[26:29], v[142:145], v[126:129], v[26:29]
	ds_read_b128 v[138:141], v0 offset:55296
	ds_read_b128 v[142:145], v0 offset:56320
	s_waitcnt lgkmcnt(2)
	v_mfma_f32_16x16x32_bf16 v[102:105], v[130:133], v[114:117], v[102:105]
	v_mfma_f32_16x16x32_bf16 v[22:25], v[130:133], v[122:125], v[22:25]
	v_mfma_f32_16x16x32_bf16 v[102:105], v[134:137], v[118:121], v[102:105]
	v_mfma_f32_16x16x32_bf16 v[22:25], v[134:137], v[126:129], v[22:25]
	ds_read_b128 v[130:133], v0 offset:57344
	ds_read_b128 v[134:137], v0 offset:58368
	s_waitcnt lgkmcnt(2)
	v_mfma_f32_16x16x32_bf16 v[98:101], v[138:141], v[114:117], v[98:101]
	v_mfma_f32_16x16x32_bf16 v[18:21], v[138:141], v[122:125], v[18:21]
	v_mfma_f32_16x16x32_bf16 v[98:101], v[142:145], v[118:121], v[98:101]
	v_mfma_f32_16x16x32_bf16 v[18:21], v[142:145], v[126:129], v[18:21]
	ds_read_b128 v[138:141], v0 offset:59392
	ds_read_b128 v[142:145], v0 offset:60416
	s_waitcnt lgkmcnt(2)
	v_mfma_f32_16x16x32_bf16 v[90:93], v[130:133], v[114:117], v[90:93]
	v_mfma_f32_16x16x32_bf16 v[14:17], v[130:133], v[122:125], v[14:17]
	v_mfma_f32_16x16x32_bf16 v[90:93], v[134:137], v[118:121], v[90:93]
	v_mfma_f32_16x16x32_bf16 v[14:17], v[134:137], v[126:129], v[14:17]
	ds_read_b128 v[130:133], v0 offset:61440
	ds_read_b128 v[134:137], v0 offset:62464
	s_waitcnt lgkmcnt(2)
	v_mfma_f32_16x16x32_bf16 v[70:73], v[138:141], v[114:117], v[70:73]
	v_mfma_f32_16x16x32_bf16 v[10:13], v[138:141], v[122:125], v[10:13]
	v_mfma_f32_16x16x32_bf16 v[70:73], v[142:145], v[118:121], v[70:73]
	v_mfma_f32_16x16x32_bf16 v[10:13], v[142:145], v[126:129], v[10:13]
	ds_read_b128 v[138:141], v0 offset:63488
	ds_read_b128 v[142:145], v0 offset:64512
	s_waitcnt lgkmcnt(2)
	v_mfma_f32_16x16x32_bf16 v[38:41], v[130:133], v[114:117], v[38:41]
	v_mfma_f32_16x16x32_bf16 v[6:9], v[130:133], v[122:125], v[6:9]
	v_mfma_f32_16x16x32_bf16 v[38:41], v[134:137], v[118:121], v[38:41]
	v_mfma_f32_16x16x32_bf16 v[6:9], v[134:137], v[126:129], v[6:9]
	s_waitcnt lgkmcnt(0)
	v_mfma_f32_16x16x32_bf16 v[34:37], v[138:141], v[114:117], v[34:37]
	v_mfma_f32_16x16x32_bf16 v[2:5], v[138:141], v[122:125], v[2:5]
	v_mfma_f32_16x16x32_bf16 v[34:37], v[142:145], v[118:121], v[34:37]
	v_mfma_f32_16x16x32_bf16 v[2:5], v[142:145], v[126:129], v[2:5]
	s_cmp_ge_u32 s53, s43
	s_cbranch_scc1 .Lattn_lag_nodma
	s_bitcmp1_b32 s53, 0
	s_cselect_b32 s54, 0x6000, 0
	s_add_i32 s54, s54, 0
	v_lshl_add_u64 v[130:131], v[180:181], 0, v[166:167]
	s_add_i32 m0, s54, s23
	s_nop 0
	global_load_lds_dwordx4 v[130:131], off
	v_lshl_add_u64 v[130:131], v[178:179], 0, v[166:167]
	s_add_i32 m0, s54, s24
	s_nop 0
	global_load_lds_dwordx4 v[130:131], off
	s_add_i32 m0, s54, s25
	s_lshl_b32 s54, s44, 14
	s_add_i32 s54, s54, 0
	v_lshl_add_u64 v[130:131], v[176:177], 0, v[166:167]
	s_add_i32 s56, s54, s23
	global_load_lds_dwordx4 v[130:131], off
	v_lshl_add_u64 v[130:131], v[182:183], 0, v[166:167]
	s_add_i32 m0, s56, 0xc000
	s_add_i32 s54, s54, s24
	global_load_lds_dwordx4 v[130:131], off
	v_lshl_add_u64 v[130:131], v[184:185], 0, v[166:167]
	s_add_i32 m0, s54, 0xc000
	s_nop 0
	global_load_lds_dwordx4 v[130:131], off

.LBB0_733:
	s_setprio 0
	s_mov_b64 s[6:7], 0
	s_getreg_b32 s8, hwreg(HW_REG_XCC_ID, 0, 4)
	s_waitcnt vmcnt(0)
	s_barrier
	s_and_saveexec_b64 s[4:5], s[84:85]
	s_xor_b64 s[4:5], exec, s[4:5]
	s_cbranch_execz .LBB0_786
	v_readlane_b32 s9, v255, 21
	s_waitcnt vmcnt(0) expcnt(0) lgkmcnt(0)
	s_add_u32 s6, s94, s6
	v_mov_b32_e32 v0, s9
	ds_read_b32 v3, v0
	v_readlane_b32 s9, v255, 22
	s_addc_u32 s7, s95, s7
	s_and_b32 s52, s8, 15
	v_mov_b32_e32 v0, s9
	ds_read_b32 v2, v0
	s_waitcnt lgkmcnt(1)
	v_cmp_ne_u32_e32 vcc, 0, v3
	s_cbranch_vccnz .LBB0_749
	s_add_u32 s8, s6, 0x2f00200
	s_addc_u32 s9, s7, 0
	s_add_u32 s10, s6, 0x2f00400
	s_addc_u32 s11, s7, 0
	s_add_u32 s12, s6, 0x2f00500
	s_addc_u32 s13, s7, 0
	s_add_u32 s14, s6, 0x2f00600
	s_addc_u32 s15, s7, 0
	s_add_u32 s16, s6, 0x2f00700
	s_addc_u32 s17, s7, 0
	s_add_u32 s18, s6, 0x2f00800
	s_addc_u32 s19, s7, 0
	s_add_u32 s20, s6, 0x2f00900
	s_addc_u32 s21, s7, 0
	s_add_u32 s22, s6, 0x2f00a00
	s_addc_u32 s23, s7, 0
	s_add_u32 s24, s6, 0x2f00b00
	s_addc_u32 s25, s7, 0
	s_add_u32 s26, s6, 0x2f00c00
	s_addc_u32 s27, s7, 0
	s_add_u32 s28, s6, 0x2f00d00
	s_addc_u32 s29, s7, 0
	s_add_u32 s30, s6, 0x2f00e00
	s_addc_u32 s31, s7, 0
	s_add_u32 s34, s6, 0x2f00f00
	s_addc_u32 s35, s7, 0
	s_add_u32 s36, s6, 0x2f01000
	s_addc_u32 s37, s7, 0
	s_add_u32 s38, s6, 0x2f01100
	s_addc_u32 s39, s7, 0
	s_add_u32 s40, s6, 0x2f01200
	s_addc_u32 s41, s7, 0
	s_add_u32 s42, s6, 0x2f01300
	s_addc_u32 s43, s7, 0
	s_mov_b32 s53, 1
	s_branch .LBB0_737
